# barrier realignment, per-phase setprio flips removed, one static s_setprio 1 for waves 4-7
# speedup vs baseline: 1.0069x; 1.0009x over previous
; #define LAS __attribute__((address_space(3)))
; __device__ __forceinline__ int opaque_tid() { int t = threadIdx.x; asm volatile("" : "+v"(t)); return t; }
; __device__ __forceinline__ unsigned xb_add(unsigned* p, unsigned v) { return __hip_atomic_fetch_add(p, v, __ATOMIC_RELAXED, __HIP_MEMORY_SCOPE_AGENT); }
; __device__ __forceinline__ unsigned xb_xcc_id() { return (unsigned)__builtin_amdgcn_s_getreg((3 << 11) | 20) & 0xFu; }
; __device__ __forceinline__ XcdBarrier xcd_barrier_post(unsigned* bar, volatile LAS unsigned* st) {
;   XcdBarrier b; b.bar = bar; b.x = xb_xcc_id(); b.st = st;
;   if (threadIdx.x == 0) (void)xb_add(&bar[XB_XCNT(b.x)], 1u);
;   return b;
; __global__ void __launch_bounds__(512, 2) mega(Params p) {
;     ...
;   const int tid = opaque_tid(), G = gridDim.x, wv = tid >> 6, lane = tid & 63;
;   unsigned char* ws = p.ws;
;   float2* TAB = (float2*)(ws + OFF_TAB); bf16_t* DT = (bf16_t*)(ws + OFF_DFT); bf16_t* MEMB = (bf16_t*)(ws + OFF_MEMB);
;   float* RSS = (float*)(ws + OFF_RSS); bf16_t* XB = (bf16_t*)(ws + OFF_XB); bf16_t* WB = (bf16_t*)(ws + OFF_WB);
;   bf16_t* RA = (bf16_t*)(ws + OFF_A); bf16_t* RS = (bf16_t*)(ws + OFF_S); bf16_t* RB = (bf16_t*)(ws + OFF_B);
;   bf16_t* Zb = RA; bf16_t* Y1 = RA + 32 * MiB; bf16_t* GATES = RA; bf16_t* HID = RA; bf16_t* QX = RA; bf16_t* Ob = RA + 32 * MiB;
;   bf16_t* STf = RS; bf16_t* STb = RS + 32 * MiB;
;   bf16_t* Qb = RB; bf16_t* Kb = RB + 16 * MiB; bf16_t* Vb = RB + 32 * MiB; bf16_t* Fb = RB + 64 * MiB; bf16_t* Ub = RB; bf16_t* KVb = RB + 32 * MiB;
;   float* X = p.X;
;   const LAS float* RSL = (const LAS float*)(lds + 131072);
;   volatile LAS unsigned* xst = (volatile LAS unsigned*)(lds + 163824);
;   if (threadIdx.x < 4) xst[threadIdx.x] = 0u;
;   __syncthreads();
;   const XcdBarrier xb = xcd_barrier_post((unsigned*)(ws + WS_NEED), xst);
_Z4mega6Params:
	s_load_dwordx4 s[88:91], s[0:1], 0xc0
	s_load_dword s16, s[0:1], 0xd0
	s_add_u32 s6, s0, 0xc8
	v_and_b32_e32 v214, 0x3ff, v0
	s_addc_u32 s7, s1, 0
	v_mov_b32_e32 v24, v214
	v_cmp_gt_u32_e32 vcc, 4, v214
	v_readfirstlane_b32 s101, v214
	s_mov_b32 s100, 0
	s_cmp_ge_u32 s101, 0x100
	s_cbranch_scc0 .Lprio_skip
	s_setprio 1
.Lprio_skip:
	s_and_saveexec_b64 s[4:5], vcc
	v_lshl_add_u32 v1, v214, 2, 0
	v_add_u32_e32 v1, 0x27ff0, v1
	v_mov_b32_e32 v2, 0
	ds_write_b32 v1, v2
	s_or_b64 exec, exec, s[4:5]
	s_waitcnt lgkmcnt(0)
	s_barrier
	s_add_u32 s20, s88, 0x228c0000
	s_getreg_b32 s3, hwreg(HW_REG_XCC_ID, 0, 4)
	s_addc_u32 s21, s89, 0
	s_and_b32 s17, s3, 15
	v_cmp_eq_u32_e32 vcc, 0, v214
	s_and_saveexec_b64 s[4:5], vcc
	s_cbranch_execz .LBB0_5
	s_mov_b64 s[8:9], exec
	v_mbcnt_lo_u32_b32 v1, s8, 0
	v_mbcnt_hi_u32_b32 v1, s9, v1
	v_cmp_eq_u32_e32 vcc, 0, v1
	s_and_b64 s[10:11], exec, vcc
	s_mov_b64 exec, s[10:11]
	s_cbranch_execz .LBB0_5
	s_lshl_b32 s3, s17, 8
	s_bcnt1_i32_b64 s8, s[8:9]
	v_mov_b32_e32 v1, s3
	v_mov_b32_e32 v2, s8
	global_atomic_add v1, v2, s[20:21] offset:1024
